# lean GEMM load segments (no VALU in load segments) + x->bf16 prologue loop with 8 loads in flight
# baseline (speedup 1.0000x reference)
.LBB0_618:
	global_load_dwordx4 v[20:23], v[0:1], off offset:-4096
	global_load_dwordx4 v[24:27], v[0:1], off offset:-3072
	global_load_dwordx4 v[28:31], v[0:1], off offset:-2048
	global_load_dwordx4 v[32:35], v[0:1], off offset:-1024
	global_load_dwordx4 v[36:39], v[0:1], off
	global_load_dwordx4 v[40:43], v[0:1], off offset:1024
	global_load_dwordx4 v[44:47], v[0:1], off offset:2048
	global_load_dwordx4 v[48:51], v[0:1], off offset:3072
	s_waitcnt lgkmcnt(0)
	v_lshl_add_u64 v[4:5], s[94:95], 0, v[2:3]
	s_mov_b32 s1, 0x10800000
	v_add_co_u32_e32 v4, vcc, s1, v4
	s_nop 1
	v_addc_co_u32_e32 v5, vcc, 0, v5, vcc
	s_waitcnt vmcnt(7)
	v_mul_f32_e32 v16, v21, v21
	v_fmac_f32_e32 v16, v20, v20
	v_mul_f32_e32 v17, v23, v23
	v_fmac_f32_e32 v17, v22, v22
	v_add_f32_e32 v16, v16, v17
	v_cvt_pk_bf16_f32 v12, v20, v21
	v_cvt_pk_bf16_f32 v13, v22, v23
	global_store_dwordx2 v[4:5], v[12:13], off
	s_waitcnt vmcnt(7)
	v_mul_f32_e32 v17, v25, v25
	v_fmac_f32_e32 v17, v24, v24
	v_mul_f32_e32 v18, v27, v27
	v_fmac_f32_e32 v18, v26, v26
	v_add_f32_e32 v17, v17, v18
	v_add_f32_e32 v16, v16, v17
	v_cvt_pk_bf16_f32 v14, v24, v25
	v_cvt_pk_bf16_f32 v15, v26, v27
	global_store_dwordx2 v[4:5], v[14:15], off offset:512
	s_waitcnt vmcnt(7)
	v_mul_f32_e32 v17, v29, v29
	v_fmac_f32_e32 v17, v28, v28
	v_mul_f32_e32 v18, v31, v31
	v_fmac_f32_e32 v18, v30, v30
	v_add_f32_e32 v17, v17, v18
	v_add_f32_e32 v16, v16, v17
	v_cvt_pk_bf16_f32 v12, v28, v29
	v_cvt_pk_bf16_f32 v13, v30, v31
	global_store_dwordx2 v[4:5], v[12:13], off offset:1024
	s_waitcnt vmcnt(7)
	v_mul_f32_e32 v17, v33, v33
	v_fmac_f32_e32 v17, v32, v32
	v_mul_f32_e32 v18, v35, v35
	v_fmac_f32_e32 v18, v34, v34
	v_add_f32_e32 v17, v17, v18
	v_add_f32_e32 v16, v16, v17
	v_cvt_pk_bf16_f32 v14, v32, v33
	v_cvt_pk_bf16_f32 v15, v34, v35
	global_store_dwordx2 v[4:5], v[14:15], off offset:1536
	s_waitcnt vmcnt(7)
	v_mul_f32_e32 v17, v37, v37
	v_fmac_f32_e32 v17, v36, v36
	v_mul_f32_e32 v18, v39, v39
	v_fmac_f32_e32 v18, v38, v38
	v_add_f32_e32 v17, v17, v18
	v_add_f32_e32 v16, v16, v17
	v_cvt_pk_bf16_f32 v12, v36, v37
	v_cvt_pk_bf16_f32 v13, v38, v39
	global_store_dwordx2 v[4:5], v[12:13], off offset:2048
	s_waitcnt vmcnt(7)
	v_mul_f32_e32 v17, v41, v41
	v_fmac_f32_e32 v17, v40, v40
	v_mul_f32_e32 v18, v43, v43
	v_fmac_f32_e32 v18, v42, v42
	v_add_f32_e32 v17, v17, v18
	v_add_f32_e32 v16, v16, v17
	v_cvt_pk_bf16_f32 v14, v40, v41
	v_cvt_pk_bf16_f32 v15, v42, v43
	global_store_dwordx2 v[4:5], v[14:15], off offset:2560
	s_waitcnt vmcnt(7)
	v_mul_f32_e32 v17, v45, v45
	v_fmac_f32_e32 v17, v44, v44
	v_mul_f32_e32 v18, v47, v47
	v_fmac_f32_e32 v18, v46, v46
	v_add_f32_e32 v17, v17, v18
	v_add_f32_e32 v16, v16, v17
	v_cvt_pk_bf16_f32 v12, v44, v45
	v_cvt_pk_bf16_f32 v13, v46, v47
	global_store_dwordx2 v[4:5], v[12:13], off offset:3072
	s_waitcnt vmcnt(7)
	v_mul_f32_e32 v17, v49, v49
	v_fmac_f32_e32 v17, v48, v48
	v_mul_f32_e32 v18, v51, v51
	v_fmac_f32_e32 v18, v50, v50
	v_add_f32_e32 v17, v17, v18
	v_add_f32_e32 v16, v16, v17
	v_cvt_pk_bf16_f32 v14, v48, v49
	v_cvt_pk_bf16_f32 v15, v50, v51
	global_store_dwordx2 v[4:5], v[14:15], off offset:3584
	ds_bpermute_b32 v4, v6, v16
	s_waitcnt lgkmcnt(0)
	v_add_f32_e32 v4, v16, v4
	ds_bpermute_b32 v5, v7, v4
	s_waitcnt lgkmcnt(0)
	v_add_f32_e32 v4, v4, v5
	ds_bpermute_b32 v5, v8, v4
	s_waitcnt lgkmcnt(0)
	v_add_f32_e32 v4, v4, v5
	ds_bpermute_b32 v5, v9, v4
	s_waitcnt lgkmcnt(0)
	v_add_f32_e32 v4, v4, v5
	ds_bpermute_b32 v5, v10, v4
	s_waitcnt lgkmcnt(0)
	v_add_f32_e32 v4, v4, v5
	ds_bpermute_b32 v5, v11, v4
	s_and_saveexec_b64 s[16:17], s[6:7]
	s_cbranch_execz .LBB0_617
	s_add_u32 s18, s94, s2
	s_waitcnt lgkmcnt(0)
	v_add_f32_e32 v4, v4, v5
	s_addc_u32 s19, s95, s5
	global_store_dword v65, v4, s[18:19]
	s_branch .LBB0_617
